# bh2 + GEMM phases: one static s_setprio 1 for waves 0-3 (leading group), per-segment flips deleted
# speedup vs baseline: 1.0054x; 1.0008x over previous
; template <class Epi, class Sched, bool SEG3 = false>
; __device__ __forceinline__ void gemm_phase(PG8_LAS unsigned char* lds, const Gemm g, const Sched& S, const Epi& E) {
;     ...
;     const int tid = tid_, wid = __builtin_amdgcn_readfirstlane(tid >> 6), lane = tid & 63, wr = wid >> 2, wc = wid & 3, fr = lane & 15, fq = lane >> 4;
.LBB0_413:
	s_mov_b32 s98, 0
	v_readfirstlane_b32 s99, v0
	s_nop 3
	s_lshr_b32 s99, s99, 6
	s_cmp_lt_u32 s99, 4
	s_cbranch_scc0 .Lprio_done_4
	s_setprio 1
